# P6 tail: the four final-norm weight loads requested before the row-sum exchange poll (the second pair no longer waits behind the first half's 16 output stores); on top of v52
# speedup vs baseline: 1.0079x; 1.0079x over previous
;     __device__ __forceinline__ bool run(const f32x4 (&v)[2][2][4][2], const Unit& u, int wr, int wc, int fr, int fq, PG8_LAS unsigned char* lds, int wid, int lane) const {
;     ...
;         asm volatile("s_waitcnt vmcnt(0) lgkmcnt(0)" ::: "memory"); __builtin_amdgcn_s_barrier(); asm volatile("" ::: "memory");
;         const bool bad = flag[0] != 0u;
;         if (lane < 32) {
;             const unsigned long long* slot = (const unsigned long long*)xbuf + (size_t)(u.pm * BM + row) * 4; float q = 0.f;
; #pragma unroll
;             for (int t = 0; t < 4; ++t) if (t < ntn) { const unsigned long long w = __hip_atomic_load(slot + t, __ATOMIC_RELAXED, __HIP_MEMORY_SCOPE_AGENT); q += __uint_as_float((unsigned)w); }
;             S[row] = 1.0f / sqrtf(q / (256.0f * (float)ntn) + eps);
;     __device__ __forceinline__ void fused(f32x4 (&acc)[2][2][4][2], const Unit& u, int wr, int wc, int fr, int fq, PG8_LAS unsigned char* lds, int wid, int lane) const {
;     ...
;             const f32x4 w0 = *(const f32x4*)(fw + col0 + bj * HALF), w1 = *(const f32x4*)(fw + col0 + bj * HALF + 4);
.LBB0_1031:
	s_waitcnt lgkmcnt(0)
	s_barrier
	v_lshlrev_b64 v[182:183], 2, v[144:145]
	v_lshl_add_u64 v[182:183], s[56:57], 0, v[182:183]
	global_load_dwordx4 v[166:169], v[182:183], off
	global_load_dwordx4 v[170:173], v[182:183], off offset:16
	global_load_dwordx4 v[174:177], v[182:183], off offset:512
	global_load_dwordx4 v[178:181], v[182:183], off offset:528
	v_mov_b32_e32 v130, 0
	ds_read_b32 v140, v130 offset:10240
	s_and_saveexec_b64 s[2:3], s[0:1]
	s_cbranch_execz .LBB0_1033
	v_lshlrev_b64 v[128:129], 5, v[128:129]
	v_lshl_add_u64 v[128:129], s[8:9], 0, v[128:129]
	s_mov_b32 s6, 0

;     __device__ __forceinline__ void fused(f32x4 (&acc)[2][2][4][2], const Unit& u, int wr, int wc, int fr, int fq, PG8_LAS unsigned char* lds, int wid, int lane) const {
;     ...
; #pragma unroll
;         for (int bj = 0; bj < 2; ++bj) {
;             const f32x4 w0 = *(const f32x4*)(fw + col0 + bj * HALF), w1 = *(const f32x4*)(fw + col0 + bj * HALF + 4);
; #pragma unroll
;             for (int ai = 0; ai < 2; ++ai)
; #pragma unroll
;                 for (int m = 0; m < 4; ++m) { const int r = ai * HALF + wr * 64 + m * 16 + fr; const float sr = S[r]; const size_t off = (size_t)(u.pm * BM + r) * 1024 + col0 + bj * HALF;
;                     f32x4 o0 = acc[ai][bj][m][0] * sr * w0, o1 = acc[ai][bj][m][1] * sr * w1;
;                     if (bad) { o0 = (f32x4){qnan, qnan, qnan, qnan}; o1 = o0; }
;                     *(f32x4*)(out + off) = o0; *(f32x4*)(out + off + 4) = o1; } }
.LBB0_1033:
	s_or_b64 exec, exec, s[2:3]
	v_lshlrev_b64 v[136:137], 2, v[144:145]
	s_waitcnt lgkmcnt(0)
	s_barrier
	v_lshl_add_u64 v[138:139], s[56:57], 0, v[136:137]
	s_waitcnt vmcnt(0)
	v_mov_b32_e32 v132, v166
	v_mov_b32_e32 v133, v167
	v_mov_b32_e32 v134, v168
	v_mov_b32_e32 v135, v169
	v_mov_b32_e32 v128, v170
	v_mov_b32_e32 v129, v171
	v_mov_b32_e32 v130, v172
	v_mov_b32_e32 v131, v173
	v_lshl_add_u32 v143, v149, 2, 0
	s_waitcnt lgkmcnt(0)
	v_or_b32_e32 v150, v140, v148
	v_add_u32_e32 v140, s16, v149
	v_add_u32_e32 v149, 0x2000, v143
	ds_read_b32 v144, v143 offset:8192
	ds_read_b32 v148, v143 offset:8896
	ds_read2_b32 v[154:155], v149 offset1:16
	v_mov_b32_e32 v145, 0x7fc00000
	v_ashrrev_i32_e32 v141, 31, v140
	v_add_u32_e32 v142, 16, v140
	ds_read2_b32 v[156:157], v149 offset0:16 offset1:32
	v_lshlrev_b64 v[152:153], 12, v[140:141]
	v_ashrrev_i32_e32 v143, 31, v142
	s_waitcnt lgkmcnt(3)
	v_pk_mul_f32 v[58:59], v[58:59], v[144:145] op_sel_hi:[1,0]
	v_pk_mul_f32 v[56:57], v[56:57], v[144:145] op_sel_hi:[1,0]
	v_pk_mul_f32 v[62:63], v[62:63], v[144:145] op_sel_hi:[1,0]
	v_pk_mul_f32 v[60:61], v[60:61], v[144:145] op_sel_hi:[1,0]
	s_waitcnt lgkmcnt(1)
	v_mov_b32_e32 v144, v155
	v_lshl_add_u64 v[158:159], s[58:59], 0, v[152:153]
	v_lshlrev_b64 v[142:143], 12, v[142:143]
	v_pk_mul_f32 v[86:87], v[86:87], v[144:145] op_sel_hi:[1,0]
	v_pk_mul_f32 v[84:85], v[84:85], v[144:145] op_sel_hi:[1,0]
	v_pk_mul_f32 v[90:91], v[90:91], v[144:145] op_sel_hi:[1,0]
	v_pk_mul_f32 v[88:89], v[88:89], v[144:145] op_sel_hi:[1,0]
	v_cmp_ne_u32_e32 vcc, 0, v150
	v_lshl_add_u64 v[158:159], v[158:159], 0, v[136:137]
	v_lshl_add_u64 v[160:161], s[58:59], 0, v[142:143]
	v_add_u32_e32 v146, 32, v140
	v_lshl_add_u64 v[160:161], v[160:161], 0, v[136:137]
	v_ashrrev_i32_e32 v147, 31, v146
	s_waitcnt lgkmcnt(0)
	v_mov_b32_e32 v164, v157
	v_lshlrev_b64 v[146:147], 12, v[146:147]
	v_pk_mul_f32 v[106:107], v[106:107], v[164:165] op_sel_hi:[1,0]
	v_pk_mul_f32 v[104:105], v[104:105], v[164:165] op_sel_hi:[1,0]
	v_lshl_add_u64 v[162:163], s[58:59], 0, v[146:147]
	v_pk_mul_f32 v[110:111], v[110:111], v[164:165] op_sel_hi:[1,0]
	v_pk_mul_f32 v[108:109], v[108:109], v[164:165] op_sel_hi:[1,0]
	v_lshl_add_u64 v[162:163], v[162:163], 0, v[136:137]
	v_pk_mul_f32 v[2:3], v[2:3], v[148:149] op_sel_hi:[1,0]
	v_pk_mul_f32 v[0:1], v[0:1], v[148:149] op_sel_hi:[1,0]
	v_pk_mul_f32 v[6:7], v[6:7], v[148:149] op_sel_hi:[1,0]
	v_pk_mul_f32 v[4:5], v[4:5], v[148:149] op_sel_hi:[1,0]
	s_waitcnt vmcnt(1)
	v_pk_mul_f32 v[56:57], v[132:133], v[56:57]
	v_pk_mul_f32 v[58:59], v[134:135], v[58:59]
	s_waitcnt vmcnt(0)
	v_pk_mul_f32 v[60:61], v[128:129], v[60:61]
	v_pk_mul_f32 v[62:63], v[130:131], v[62:63]
	v_pk_mul_f32 v[84:85], v[132:133], v[84:85]
	v_pk_mul_f32 v[86:87], v[134:135], v[86:87]
	v_pk_mul_f32 v[88:89], v[128:129], v[88:89]
	v_pk_mul_f32 v[90:91], v[130:131], v[90:91]
	v_cndmask_b32_e32 v59, v59, v145, vcc
	v_cndmask_b32_e32 v58, v58, v145, vcc
	v_cndmask_b32_e32 v57, v57, v145, vcc
	v_cndmask_b32_e32 v56, v56, v145, vcc
	v_cndmask_b32_e32 v63, v63, v145, vcc
	v_cndmask_b32_e32 v62, v62, v145, vcc
	v_cndmask_b32_e32 v61, v61, v145, vcc
	v_cndmask_b32_e32 v60, v60, v145, vcc
	v_cndmask_b32_e32 v87, v87, v145, vcc
	v_cndmask_b32_e32 v86, v86, v145, vcc
	v_cndmask_b32_e32 v85, v85, v145, vcc
	v_cndmask_b32_e32 v84, v84, v145, vcc
	v_cndmask_b32_e32 v91, v91, v145, vcc
	v_cndmask_b32_e32 v90, v90, v145, vcc
	v_cndmask_b32_e32 v89, v89, v145, vcc
	v_cndmask_b32_e32 v88, v88, v145, vcc
	global_store_dwordx4 v[158:159], v[56:59], off
	global_store_dwordx4 v[158:159], v[60:63], off offset:16
	global_store_dwordx4 v[160:161], v[84:87], off
	global_store_dwordx4 v[160:161], v[88:91], off offset:16
	ds_read2_b32 v[84:85], v149 offset0:32 offset1:48
	v_pk_mul_f32 v[104:105], v[132:133], v[104:105]
	v_pk_mul_f32 v[106:107], v[134:135], v[106:107]
	v_pk_mul_f32 v[108:109], v[128:129], v[108:109]
	v_pk_mul_f32 v[110:111], v[130:131], v[110:111]
	v_cndmask_b32_e32 v107, v107, v145, vcc
	v_cndmask_b32_e32 v106, v106, v145, vcc
	v_cndmask_b32_e32 v105, v105, v145, vcc
	v_cndmask_b32_e32 v104, v104, v145, vcc
	v_cndmask_b32_e32 v111, v111, v145, vcc
	v_cndmask_b32_e32 v110, v110, v145, vcc
	v_cndmask_b32_e32 v109, v109, v145, vcc
	v_cndmask_b32_e32 v108, v108, v145, vcc
	global_store_dwordx4 v[162:163], v[104:107], off
	global_store_dwordx4 v[162:163], v[108:111], off offset:16
	v_add_u32_e32 v86, 48, v140
	s_waitcnt lgkmcnt(0)
	v_mov_b32_e32 v56, v85
	ds_read2_b32 v[90:91], v149 offset0:48 offset1:128
	v_ashrrev_i32_e32 v87, 31, v86
	v_pk_mul_f32 v[58:59], v[126:127], v[56:57] op_sel_hi:[1,0]
	v_pk_mul_f32 v[60:61], v[124:125], v[56:57] op_sel_hi:[1,0]
	v_pk_mul_f32 v[62:63], v[122:123], v[56:57] op_sel_hi:[1,0]
	v_pk_mul_f32 v[56:57], v[120:121], v[56:57] op_sel_hi:[1,0]
	v_pk_mul_f32 v[60:61], v[132:133], v[60:61]
	v_pk_mul_f32 v[88:89], v[128:129], v[56:57]
	v_lshlrev_b64 v[86:87], 12, v[86:87]
	v_pk_mul_f32 v[58:59], v[134:135], v[58:59]
	v_cndmask_b32_e32 v57, v61, v145, vcc
	v_cndmask_b32_e32 v56, v60, v145, vcc
	v_cndmask_b32_e32 v61, v89, v145, vcc
	v_cndmask_b32_e32 v60, v88, v145, vcc
	v_lshl_add_u64 v[88:89], s[58:59], 0, v[86:87]
	v_pk_mul_f32 v[62:63], v[130:131], v[62:63]
	v_cndmask_b32_e32 v59, v59, v145, vcc
	v_cndmask_b32_e32 v58, v58, v145, vcc
	v_lshl_add_u64 v[88:89], v[88:89], 0, v[136:137]
	v_cndmask_b32_e32 v63, v63, v145, vcc
	v_cndmask_b32_e32 v62, v62, v145, vcc
	global_store_dwordx4 v[88:89], v[56:59], off
	global_store_dwordx4 v[88:89], v[60:63], off offset:16
	v_add_u32_e32 v88, 0x80, v140
	s_waitcnt lgkmcnt(0)
;     __device__ __forceinline__ void fused(f32x4 (&acc)[2][2][4][2], const Unit& u, int wr, int wc, int fr, int fq, PG8_LAS unsigned char* lds, int wid, int lane) const {
;     ...
; #pragma unroll
;         for (int bj = 0; bj < 2; ++bj) {
;             const f32x4 w0 = *(const f32x4*)(fw + col0 + bj * HALF), w1 = *(const f32x4*)(fw + col0 + bj * HALF + 4);
; #pragma unroll
;             for (int ai = 0; ai < 2; ++ai)
; #pragma unroll
;                 for (int m = 0; m < 4; ++m) { const int r = ai * HALF + wr * 64 + m * 16 + fr; const float sr = S[r]; const size_t off = (size_t)(u.pm * BM + r) * 1024 + col0 + bj * HALF;
;                     f32x4 o0 = acc[ai][bj][m][0] * sr * w0, o1 = acc[ai][bj][m][1] * sr * w1;
;                     if (bad) { o0 = (f32x4){qnan, qnan, qnan, qnan}; o1 = o0; }
;                     *(f32x4*)(out + off) = o0; *(f32x4*)(out + off + 4) = o1; } }
	v_mov_b32_e32 v56, v91
	v_pk_mul_f32 v[58:59], v[94:95], v[56:57] op_sel_hi:[1,0]
	v_pk_mul_f32 v[60:61], v[92:93], v[56:57] op_sel_hi:[1,0]
	v_pk_mul_f32 v[62:63], v[82:83], v[56:57] op_sel_hi:[1,0]
	v_pk_mul_f32 v[56:57], v[80:81], v[56:57] op_sel_hi:[1,0]
	v_ashrrev_i32_e32 v89, 31, v88
	v_pk_mul_f32 v[60:61], v[132:133], v[60:61]
	v_pk_mul_f32 v[80:81], v[128:129], v[56:57]
	v_cndmask_b32_e32 v57, v61, v145, vcc
	v_cndmask_b32_e32 v56, v60, v145, vcc
	v_cndmask_b32_e32 v61, v81, v145, vcc
	v_cndmask_b32_e32 v60, v80, v145, vcc
	v_lshlrev_b64 v[80:81], 12, v[88:89]
	ds_read2_b32 v[88:89], v149 offset0:128 offset1:144
	v_pk_mul_f32 v[58:59], v[134:135], v[58:59]
	v_lshl_add_u64 v[82:83], s[58:59], 0, v[80:81]
	v_pk_mul_f32 v[62:63], v[130:131], v[62:63]
	v_cndmask_b32_e32 v59, v59, v145, vcc
	v_cndmask_b32_e32 v58, v58, v145, vcc
	v_lshl_add_u64 v[82:83], v[82:83], 0, v[136:137]
	v_cndmask_b32_e32 v63, v63, v145, vcc
	v_cndmask_b32_e32 v62, v62, v145, vcc
	global_store_dwordx4 v[82:83], v[56:59], off
	global_store_dwordx4 v[82:83], v[60:63], off offset:16
	s_waitcnt lgkmcnt(0)
	v_mov_b32_e32 v58, v89
	v_pk_mul_f32 v[54:55], v[54:55], v[58:59] op_sel_hi:[1,0]
	v_pk_mul_f32 v[50:51], v[50:51], v[58:59] op_sel_hi:[1,0]
	v_pk_mul_f32 v[54:55], v[134:135], v[54:55]
	v_pk_mul_f32 v[60:61], v[130:131], v[50:51]
	v_add_u32_e32 v56, 0x90, v140
	v_cndmask_b32_e32 v51, v55, v145, vcc
	v_cndmask_b32_e32 v50, v54, v145, vcc
	v_cndmask_b32_e32 v55, v61, v145, vcc
	v_cndmask_b32_e32 v54, v60, v145, vcc
	ds_read2_b32 v[60:61], v149 offset0:144 offset1:160
	v_ashrrev_i32_e32 v57, 31, v56
	v_pk_mul_f32 v[52:53], v[52:53], v[58:59] op_sel_hi:[1,0]
	v_pk_mul_f32 v[48:49], v[48:49], v[58:59] op_sel_hi:[1,0]
	v_pk_mul_f32 v[52:53], v[132:133], v[52:53]
	v_pk_mul_f32 v[58:59], v[128:129], v[48:49]
	v_lshlrev_b64 v[56:57], 12, v[56:57]
	v_cndmask_b32_e32 v49, v53, v145, vcc
	v_cndmask_b32_e32 v48, v52, v145, vcc
	v_cndmask_b32_e32 v53, v59, v145, vcc
	v_cndmask_b32_e32 v52, v58, v145, vcc
	v_lshl_add_u64 v[58:59], s[58:59], 0, v[56:57]
	v_lshl_add_u64 v[58:59], v[58:59], 0, v[136:137]
	global_store_dwordx4 v[58:59], v[48:51], off
	global_store_dwordx4 v[58:59], v[52:55], off offset:16
	s_waitcnt lgkmcnt(0)
	v_mov_b32_e32 v50, v61
	v_pk_mul_f32 v[30:31], v[30:31], v[50:51] op_sel_hi:[1,0]
	v_pk_mul_f32 v[26:27], v[26:27], v[50:51] op_sel_hi:[1,0]
	v_add_u32_e32 v48, 0xa0, v140
	v_pk_mul_f32 v[30:31], v[134:135], v[30:31]
	v_pk_mul_f32 v[52:53], v[130:131], v[26:27]
	v_ashrrev_i32_e32 v49, 31, v48
	v_pk_mul_f32 v[28:29], v[28:29], v[50:51] op_sel_hi:[1,0]
	v_pk_mul_f32 v[24:25], v[24:25], v[50:51] op_sel_hi:[1,0]
	v_cndmask_b32_e32 v27, v31, v145, vcc
	v_cndmask_b32_e32 v26, v30, v145, vcc
	v_cndmask_b32_e32 v31, v53, v145, vcc
	v_cndmask_b32_e32 v30, v52, v145, vcc
	ds_read2_b32 v[52:53], v149 offset0:160 offset1:176
	v_pk_mul_f32 v[28:29], v[132:133], v[28:29]
	v_pk_mul_f32 v[50:51], v[128:129], v[24:25]
	v_lshlrev_b64 v[48:49], 12, v[48:49]
	v_cndmask_b32_e32 v25, v29, v145, vcc
	v_cndmask_b32_e32 v24, v28, v145, vcc
	v_cndmask_b32_e32 v29, v51, v145, vcc
	v_cndmask_b32_e32 v28, v50, v145, vcc
	v_lshl_add_u64 v[50:51], s[58:59], 0, v[48:49]
	v_lshl_add_u64 v[50:51], v[50:51], 0, v[136:137]
	global_store_dwordx4 v[50:51], v[24:27], off
	global_store_dwordx4 v[50:51], v[28:31], off offset:16
	s_waitcnt lgkmcnt(0)
	v_pk_mul_f32 v[18:19], v[18:19], v[52:53] op_sel_hi:[1,0]
	v_add_u32_e32 v24, 0xb0, v140
	v_ashrrev_i32_e32 v25, 31, v24
	v_mov_b32_e32 v26, v53
	v_pk_mul_f32 v[14:15], v[14:15], v[26:27] op_sel_hi:[1,0]
	v_pk_mul_f32 v[12:13], v[12:13], v[26:27] op_sel_hi:[1,0]
	v_lshlrev_b64 v[50:51], 12, v[24:25]
	v_pk_mul_f32 v[12:13], v[132:133], v[12:13]
	v_pk_mul_f32 v[14:15], v[134:135], v[14:15]
	v_pk_mul_f32 v[10:11], v[10:11], v[26:27] op_sel_hi:[1,0]
	v_pk_mul_f32 v[8:9], v[8:9], v[26:27] op_sel_hi:[1,0]
	v_lshl_add_u64 v[24:25], s[58:59], 0, v[50:51]
	v_pk_mul_f32 v[26:27], v[128:129], v[8:9]
	v_pk_mul_f32 v[28:29], v[130:131], v[10:11]
	v_cndmask_b32_e32 v11, v15, v145, vcc
	v_cndmask_b32_e32 v10, v14, v145, vcc
	v_cndmask_b32_e32 v9, v13, v145, vcc
	v_cndmask_b32_e32 v8, v12, v145, vcc
	v_lshl_add_u64 v[24:25], v[24:25], 0, v[136:137]
	v_cndmask_b32_e32 v15, v29, v145, vcc
	v_cndmask_b32_e32 v14, v28, v145, vcc
	v_cndmask_b32_e32 v13, v27, v145, vcc
	v_cndmask_b32_e32 v12, v26, v145, vcc
	global_store_dwordx4 v[24:25], v[8:11], off
	global_store_dwordx4 v[24:25], v[12:15], off offset:16
	s_nop 1
	v_mov_b32_e32 v8, v174
	v_mov_b32_e32 v9, v175
	v_mov_b32_e32 v10, v176
	v_mov_b32_e32 v11, v177
	s_nop 0
	v_mov_b32_e32 v12, v178
	v_mov_b32_e32 v13, v179
	v_mov_b32_e32 v14, v180
	v_mov_b32_e32 v15, v181
	v_pk_mul_f32 v[24:25], v[34:35], v[154:155] op_sel_hi:[1,0]
	v_pk_mul_f32 v[26:27], v[32:33], v[154:155] op_sel_hi:[1,0]
	v_pk_mul_f32 v[30:31], v[36:37], v[154:155] op_sel_hi:[1,0]
	v_pk_mul_f32 v[16:17], v[16:17], v[52:53] op_sel_hi:[1,0]
	v_pk_mul_f32 v[22:23], v[22:23], v[52:53] op_sel_hi:[1,0]
	v_pk_mul_f32 v[20:21], v[20:21], v[52:53] op_sel_hi:[1,0]
	s_nop 0
	v_pk_mul_f32 v[28:29], v[8:9], v[26:27]
	v_pk_mul_f32 v[24:25], v[10:11], v[24:25]
	v_pk_mul_f32 v[26:27], v[38:39], v[154:155] op_sel_hi:[1,0]
	s_nop 0
	v_pk_mul_f32 v[32:33], v[12:13], v[30:31]
	v_pk_mul_f32 v[30:31], v[14:15], v[26:27]
	v_cndmask_b32_e32 v27, v25, v145, vcc
	v_cndmask_b32_e32 v26, v24, v145, vcc
	v_cndmask_b32_e32 v25, v29, v145, vcc
	v_cndmask_b32_e32 v24, v28, v145, vcc
	v_cndmask_b32_e32 v29, v33, v145, vcc
	v_cndmask_b32_e32 v28, v32, v145, vcc
	v_lshl_add_u64 v[32:33], s[58:59], 0, v[136:137]
	v_cndmask_b32_e32 v31, v31, v145, vcc
	v_cndmask_b32_e32 v30, v30, v145, vcc
;     __device__ __forceinline__ void fused(f32x4 (&acc)[2][2][4][2], const Unit& u, int wr, int wc, int fr, int fq, PG8_LAS unsigned char* lds, int wid, int lane) const {
;     ...
; #pragma unroll
;         for (int bj = 0; bj < 2; ++bj) {
;             const f32x4 w0 = *(const f32x4*)(fw + col0 + bj * HALF), w1 = *(const f32x4*)(fw + col0 + bj * HALF + 4);
; #pragma unroll
;             for (int ai = 0; ai < 2; ++ai)
; #pragma unroll
;                 for (int m = 0; m < 4; ++m) { const int r = ai * HALF + wr * 64 + m * 16 + fr; const float sr = S[r]; const size_t off = (size_t)(u.pm * BM + r) * 1024 + col0 + bj * HALF;
;                     f32x4 o0 = acc[ai][bj][m][0] * sr * w0, o1 = acc[ai][bj][m][1] * sr * w1;
;                     if (bad) { o0 = (f32x4){qnan, qnan, qnan, qnan}; o1 = o0; }
;                     *(f32x4*)(out + off) = o0; *(f32x4*)(out + off + 4) = o1; } }
	v_lshl_add_u64 v[34:35], v[32:33], 0, v[152:153]
	global_store_dwordx4 v[34:35], v[24:27], off offset:512
	global_store_dwordx4 v[34:35], v[28:31], off offset:528
	v_pk_mul_f32 v[16:17], v[8:9], v[16:17]
	v_pk_mul_f32 v[24:25], v[66:67], v[156:157] op_sel_hi:[1,0]
	v_pk_mul_f32 v[26:27], v[64:65], v[156:157] op_sel_hi:[1,0]
	v_pk_mul_f32 v[30:31], v[68:69], v[156:157] op_sel_hi:[1,0]
	v_pk_mul_f32 v[28:29], v[8:9], v[26:27]
	v_pk_mul_f32 v[24:25], v[10:11], v[24:25]
	v_pk_mul_f32 v[26:27], v[70:71], v[156:157] op_sel_hi:[1,0]
	v_pk_mul_f32 v[34:35], v[12:13], v[30:31]
	v_pk_mul_f32 v[30:31], v[14:15], v[26:27]
	v_cndmask_b32_e32 v27, v25, v145, vcc
	v_cndmask_b32_e32 v26, v24, v145, vcc
	v_cndmask_b32_e32 v25, v29, v145, vcc
	v_cndmask_b32_e32 v24, v28, v145, vcc
	v_cndmask_b32_e32 v29, v35, v145, vcc
	v_cndmask_b32_e32 v28, v34, v145, vcc
	v_lshl_add_u64 v[34:35], v[32:33], 0, v[142:143]
	v_cndmask_b32_e32 v31, v31, v145, vcc
	v_cndmask_b32_e32 v30, v30, v145, vcc
	global_store_dwordx4 v[34:35], v[24:27], off offset:512
	global_store_dwordx4 v[34:35], v[28:31], off offset:528
	v_pk_mul_f32 v[18:19], v[10:11], v[18:19]
	v_pk_mul_f32 v[26:27], v[96:97], v[84:85] op_sel_hi:[1,0]
	v_pk_mul_f32 v[24:25], v[98:99], v[84:85] op_sel_hi:[1,0]
	v_pk_mul_f32 v[28:29], v[8:9], v[26:27]
	v_pk_mul_f32 v[26:27], v[102:103], v[84:85] op_sel_hi:[1,0]
	v_pk_mul_f32 v[30:31], v[100:101], v[84:85] op_sel_hi:[1,0]
	v_pk_mul_f32 v[24:25], v[10:11], v[24:25]
	v_pk_mul_f32 v[34:35], v[12:13], v[30:31]
	v_pk_mul_f32 v[30:31], v[14:15], v[26:27]
	v_cndmask_b32_e32 v27, v25, v145, vcc
	v_cndmask_b32_e32 v26, v24, v145, vcc
	v_cndmask_b32_e32 v25, v29, v145, vcc
	v_cndmask_b32_e32 v24, v28, v145, vcc
	v_cndmask_b32_e32 v31, v31, v145, vcc
	v_cndmask_b32_e32 v30, v30, v145, vcc
	v_cndmask_b32_e32 v29, v35, v145, vcc
	v_cndmask_b32_e32 v28, v34, v145, vcc
	v_lshl_add_u64 v[34:35], v[32:33], 0, v[146:147]
	global_store_dwordx4 v[34:35], v[24:27], off offset:512
	global_store_dwordx4 v[34:35], v[28:31], off offset:528
	v_pk_mul_f32 v[0:1], v[8:9], v[0:1]
	v_pk_mul_f32 v[24:25], v[114:115], v[90:91] op_sel_hi:[1,0]
	v_pk_mul_f32 v[26:27], v[112:113], v[90:91] op_sel_hi:[1,0]
	v_pk_mul_f32 v[30:31], v[116:117], v[90:91] op_sel_hi:[1,0]
	v_pk_mul_f32 v[28:29], v[8:9], v[26:27]
	v_pk_mul_f32 v[24:25], v[10:11], v[24:25]
	v_pk_mul_f32 v[26:27], v[118:119], v[90:91] op_sel_hi:[1,0]
	v_pk_mul_f32 v[34:35], v[12:13], v[30:31]
	v_pk_mul_f32 v[30:31], v[14:15], v[26:27]
	v_cndmask_b32_e32 v27, v25, v145, vcc
	v_cndmask_b32_e32 v26, v24, v145, vcc
	v_cndmask_b32_e32 v25, v29, v145, vcc
	v_cndmask_b32_e32 v24, v28, v145, vcc
	v_cndmask_b32_e32 v29, v35, v145, vcc
	v_cndmask_b32_e32 v28, v34, v145, vcc
	v_lshl_add_u64 v[34:35], v[32:33], 0, v[86:87]
	v_cndmask_b32_e32 v31, v31, v145, vcc
	v_cndmask_b32_e32 v30, v30, v145, vcc
	global_store_dwordx4 v[34:35], v[24:27], off offset:512
	global_store_dwordx4 v[34:35], v[28:31], off offset:528
	v_pk_mul_f32 v[2:3], v[10:11], v[2:3]
	v_pk_mul_f32 v[26:27], v[72:73], v[88:89] op_sel_hi:[1,0]
	v_pk_mul_f32 v[24:25], v[74:75], v[88:89] op_sel_hi:[1,0]
	v_pk_mul_f32 v[28:29], v[8:9], v[26:27]
	v_pk_mul_f32 v[26:27], v[78:79], v[88:89] op_sel_hi:[1,0]
	v_pk_mul_f32 v[30:31], v[76:77], v[88:89] op_sel_hi:[1,0]
	v_pk_mul_f32 v[24:25], v[10:11], v[24:25]
	v_pk_mul_f32 v[34:35], v[12:13], v[30:31]
	v_pk_mul_f32 v[30:31], v[14:15], v[26:27]
	v_cndmask_b32_e32 v27, v25, v145, vcc
	v_cndmask_b32_e32 v26, v24, v145, vcc
	v_cndmask_b32_e32 v25, v29, v145, vcc
	v_cndmask_b32_e32 v24, v28, v145, vcc
	v_cndmask_b32_e32 v31, v31, v145, vcc
	v_cndmask_b32_e32 v30, v30, v145, vcc
	v_cndmask_b32_e32 v29, v35, v145, vcc
	v_cndmask_b32_e32 v28, v34, v145, vcc
	v_lshl_add_u64 v[34:35], v[32:33], 0, v[80:81]
	global_store_dwordx4 v[34:35], v[24:27], off offset:512
	global_store_dwordx4 v[34:35], v[28:31], off offset:528
	v_pk_mul_f32 v[20:21], v[12:13], v[20:21]
	v_pk_mul_f32 v[24:25], v[42:43], v[60:61] op_sel_hi:[1,0]
	v_pk_mul_f32 v[26:27], v[40:41], v[60:61] op_sel_hi:[1,0]
	v_pk_mul_f32 v[30:31], v[44:45], v[60:61] op_sel_hi:[1,0]
	v_pk_mul_f32 v[28:29], v[8:9], v[26:27]
	v_pk_mul_f32 v[24:25], v[10:11], v[24:25]
	v_pk_mul_f32 v[26:27], v[46:47], v[60:61] op_sel_hi:[1,0]
	v_pk_mul_f32 v[34:35], v[12:13], v[30:31]
	v_pk_mul_f32 v[30:31], v[14:15], v[26:27]
	v_cndmask_b32_e32 v27, v25, v145, vcc
	v_cndmask_b32_e32 v26, v24, v145, vcc
	v_cndmask_b32_e32 v25, v29, v145, vcc
	v_cndmask_b32_e32 v24, v28, v145, vcc
	v_cndmask_b32_e32 v29, v35, v145, vcc
	v_cndmask_b32_e32 v28, v34, v145, vcc
	v_lshl_add_u64 v[34:35], v[32:33], 0, v[56:57]
	v_cndmask_b32_e32 v31, v31, v145, vcc
	v_cndmask_b32_e32 v30, v30, v145, vcc
	global_store_dwordx4 v[34:35], v[24:27], off offset:512
	global_store_dwordx4 v[34:35], v[28:31], off offset:528
	v_pk_mul_f32 v[22:23], v[14:15], v[22:23]
	v_cndmask_b32_e32 v19, v19, v145, vcc
	v_cndmask_b32_e32 v18, v18, v145, vcc
	v_cndmask_b32_e32 v17, v17, v145, vcc
	v_cndmask_b32_e32 v16, v16, v145, vcc
	v_lshl_add_u64 v[24:25], v[32:33], 0, v[48:49]
	v_pk_mul_f32 v[4:5], v[12:13], v[4:5]
	v_pk_mul_f32 v[6:7], v[14:15], v[6:7]
	v_cndmask_b32_e32 v3, v3, v145, vcc
	v_cndmask_b32_e32 v2, v2, v145, vcc
	v_cndmask_b32_e32 v1, v1, v145, vcc
	v_cndmask_b32_e32 v0, v0, v145, vcc
	v_lshl_add_u64 v[8:9], v[32:33], 0, v[50:51]
	v_cndmask_b32_e32 v23, v23, v145, vcc
	v_cndmask_b32_e32 v22, v22, v145, vcc
	v_cndmask_b32_e32 v21, v21, v145, vcc
	v_cndmask_b32_e32 v20, v20, v145, vcc
	global_store_dwordx4 v[24:25], v[16:19], off offset:512
	global_store_dwordx4 v[24:25], v[20:23], off offset:528
	v_cndmask_b32_e32 v7, v7, v145, vcc
	v_cndmask_b32_e32 v6, v6, v145, vcc
	v_cndmask_b32_e32 v5, v5, v145, vcc
	v_cndmask_b32_e32 v4, v4, v145, vcc
	global_store_dwordx4 v[8:9], v[0:3], off offset:512
	global_store_dwordx4 v[8:9], v[4:7], off offset:528
